# UQ and UKV gemm_phase epilogues: 16 dwordx2 -> 8 dwordx4 stores via permlane16_swap
# speedup vs baseline: 1.0132x; 1.0078x over previous
.LBB0_1296:
	s_mul_hi_i32 s0, s4, 0x55555556
	s_lshr_b32 s1, s0, 31
	s_add_i32 s0, s0, s1
	s_mul_i32 s1, s0, -3
	s_lshl_b32 s2, s0, 7
	s_add_i32 s1, s1, s4
	s_ashr_i32 s3, s2, 31
	s_lshl_b32 s0, s1, 7
	s_lshl_b64 s[6:7], s[2:3], 12
	s_ashr_i32 s1, s0, 31
	v_lshl_add_u64 v[6:7], v[80:81], 0, s[6:7]
	s_lshl_b64 s[6:7], s[0:1], 9
	v_lshl_add_u64 v[0:1], v[6:7], 0, v[84:85]
	v_lshl_add_u64 v[4:5], v[6:7], 0, v[88:89]
	v_lshl_add_u64 v[2:3], v[6:7], 0, v[92:93]
	v_lshl_add_u64 v[10:11], v[6:7], 0, v[96:97]
	v_lshl_add_u64 v[6:7], v[82:83], 0, s[6:7]
	v_lshl_add_u64 v[14:15], v[6:7], 0, v[86:87]
	global_load_dwordx4 v[16:19], v[0:1], off offset:1568
	global_load_dwordx4 v[20:23], v[4:5], off offset:1568
	global_load_dwordx4 v[24:27], v[2:3], off offset:1568
	global_load_dwordx4 v[28:31], v[10:11], off offset:1568
	v_lshl_add_u64 v[12:13], v[6:7], 0, v[90:91]
	s_waitcnt vmcnt(4)
	v_lshl_add_u64 v[8:9], v[6:7], 0, v[94:95]
	v_lshl_add_u64 v[6:7], v[6:7], 0, v[98:99]
	global_load_dwordx4 v[32:35], v[14:15], off
	global_load_dwordx4 v[36:39], v[12:13], off
	global_load_dwordx4 v[40:43], v[8:9], off
	global_load_dwordx4 v[44:47], v[6:7], off
	s_barrier
	s_mov_b32 s1, s5
	s_waitcnt vmcnt(7)
	ds_write_b128 v104, v[16:19]
	s_waitcnt vmcnt(6)
	ds_write_b128 v105, v[20:23]
	s_waitcnt vmcnt(5)
	ds_write_b128 v106, v[24:27]
	s_waitcnt vmcnt(4)
	ds_write_b128 v107, v[28:31]
	s_waitcnt vmcnt(3)
	ds_write_b128 v104, v[32:35] offset:18432
	s_waitcnt vmcnt(2)
	ds_write_b128 v105, v[36:39] offset:18432
	s_waitcnt vmcnt(1)
	ds_write_b128 v106, v[40:43] offset:18432
	s_waitcnt vmcnt(0)
	ds_write_b128 v107, v[44:47] offset:18432
	s_waitcnt lgkmcnt(0)
	s_barrier
	ds_read_b128 v[16:19], v109 offset:18432
	ds_read_b128 v[20:23], v108
	ds_read_b128 v[28:31], v109 offset:20736
	ds_read_b128 v[118:121], v109 offset:20800
	ds_read_b128 v[36:39], v109 offset:23040
	ds_read_b128 v[122:125], v109 offset:23104
	ds_read_b128 v[44:47], v109 offset:25344
	ds_read_b128 v[134:137], v109 offset:25408
	ds_read_b128 v[48:51], v108 offset:2304
	ds_read_b128 v[64:67], v108 offset:4608
	ds_read_b128 v[110:113], v108 offset:6912
	ds_read_b128 v[114:117], v109 offset:18496
	s_waitcnt lgkmcnt(10)
	v_mfma_f32_16x16x32_bf16 v[24:27], v[16:19], v[20:23], 0
	ds_read_b128 v[138:141], v108 offset:6976
	global_load_dwordx4 v[142:145], v[10:11], off offset:1696
	s_waitcnt lgkmcnt(10)
	v_mfma_f32_16x16x32_bf16 v[32:35], v[28:31], v[20:23], 0
	s_waitcnt lgkmcnt(8)
	v_mfma_f32_16x16x32_bf16 v[40:43], v[36:39], v[20:23], 0
	s_waitcnt lgkmcnt(6)
	v_mfma_f32_16x16x32_bf16 v[20:23], v[44:47], v[20:23], 0
	s_waitcnt lgkmcnt(4)
	v_mfma_f32_16x16x32_bf16 v[52:55], v[16:19], v[48:51], 0
	v_mfma_f32_16x16x32_bf16 v[56:59], v[28:31], v[48:51], 0
	v_mfma_f32_16x16x32_bf16 v[60:63], v[36:39], v[48:51], 0
	v_mfma_f32_16x16x32_bf16 v[48:51], v[44:47], v[48:51], 0
	s_waitcnt lgkmcnt(3)
	v_mfma_f32_16x16x32_bf16 v[68:71], v[16:19], v[64:67], 0
	v_mfma_f32_16x16x32_bf16 v[72:75], v[28:31], v[64:67], 0
	v_mfma_f32_16x16x32_bf16 v[76:79], v[36:39], v[64:67], 0
	v_mfma_f32_16x16x32_bf16 v[64:67], v[44:47], v[64:67], 0
	s_waitcnt lgkmcnt(2)
	v_mfma_f32_16x16x32_bf16 v[16:19], v[16:19], v[110:113], 0
	v_mfma_f32_16x16x32_bf16 v[28:31], v[28:31], v[110:113], 0
	v_mfma_f32_16x16x32_bf16 v[36:39], v[36:39], v[110:113], 0
	v_mfma_f32_16x16x32_bf16 v[44:47], v[44:47], v[110:113], 0
	ds_read_b128 v[110:113], v108 offset:64
	s_waitcnt lgkmcnt(0)
	v_mfma_f32_16x16x32_bf16 v[24:27], v[114:117], v[110:113], v[24:27]
	v_mfma_f32_16x16x32_bf16 v[32:35], v[118:121], v[110:113], v[32:35]
	v_mfma_f32_16x16x32_bf16 v[40:43], v[122:125], v[110:113], v[40:43]
	v_mfma_f32_16x16x32_bf16 v[20:23], v[134:137], v[110:113], v[20:23]
	ds_read_b128 v[110:113], v108 offset:2368
	s_waitcnt lgkmcnt(0)
	v_mfma_f32_16x16x32_bf16 v[52:55], v[114:117], v[110:113], v[52:55]
	v_mfma_f32_16x16x32_bf16 v[56:59], v[118:121], v[110:113], v[56:59]
	v_mfma_f32_16x16x32_bf16 v[60:63], v[122:125], v[110:113], v[60:63]
	v_mfma_f32_16x16x32_bf16 v[48:51], v[134:137], v[110:113], v[48:51]
	ds_read_b128 v[110:113], v108 offset:4672
	s_waitcnt lgkmcnt(0)
	v_mfma_f32_16x16x32_bf16 v[68:71], v[114:117], v[110:113], v[68:71]
	v_mfma_f32_16x16x32_bf16 v[72:75], v[118:121], v[110:113], v[72:75]
	v_mfma_f32_16x16x32_bf16 v[76:79], v[122:125], v[110:113], v[76:79]
	v_mfma_f32_16x16x32_bf16 v[64:67], v[134:137], v[110:113], v[64:67]
	global_load_dwordx4 v[110:113], v[4:5], off offset:1696
	global_load_dwordx4 v[146:149], v[0:1], off offset:1696
	global_load_dwordx4 v[150:153], v[14:15], off offset:128
	v_mfma_f32_16x16x32_bf16 v[16:19], v[114:117], v[138:141], v[16:19]
	global_load_dwordx4 v[114:117], v[12:13], off offset:128
	global_load_dwordx4 v[154:157], v[2:3], off offset:1696
	global_load_dwordx4 v[158:161], v[8:9], off offset:128
	v_mfma_f32_16x16x32_bf16 v[28:31], v[118:121], v[138:141], v[28:31]
	global_load_dwordx4 v[118:121], v[6:7], off offset:128
	s_barrier
	v_mfma_f32_16x16x32_bf16 v[36:39], v[122:125], v[138:141], v[36:39]
	s_waitcnt vmcnt(5)
	ds_write_b128 v104, v[146:149]
	s_waitcnt vmcnt(4)
	ds_write_b128 v104, v[150:153] offset:18432
	ds_write_b128 v105, v[110:113]
	s_waitcnt vmcnt(3)
	ds_write_b128 v105, v[114:117] offset:18432
	s_waitcnt vmcnt(2)
	ds_write_b128 v106, v[154:157]
	s_waitcnt vmcnt(1)
	ds_write_b128 v106, v[158:161] offset:18432
	ds_write_b128 v107, v[142:145]
	s_waitcnt vmcnt(0)
	ds_write_b128 v107, v[118:121] offset:18432
	v_mfma_f32_16x16x32_bf16 v[44:47], v[134:137], v[138:141], v[44:47]
	s_waitcnt lgkmcnt(0)
	s_barrier
	ds_read_b128 v[110:113], v109 offset:18432
	ds_read_b128 v[114:117], v108
	ds_read_b128 v[118:121], v109 offset:20736
	ds_read_b128 v[122:125], v109 offset:23040
	ds_read_b128 v[134:137], v109 offset:25344
	s_waitcnt lgkmcnt(3)
	v_mfma_f32_16x16x32_bf16 v[24:27], v[110:113], v[114:117], v[24:27]
	ds_read_b128 v[138:141], v108 offset:6976
	global_load_dwordx4 v[142:145], v[10:11], off offset:1824
	s_waitcnt lgkmcnt(3)
	v_mfma_f32_16x16x32_bf16 v[32:35], v[118:121], v[114:117], v[32:35]
	s_waitcnt lgkmcnt(2)
	v_mfma_f32_16x16x32_bf16 v[40:43], v[122:125], v[114:117], v[40:43]
	s_waitcnt lgkmcnt(1)
	v_mfma_f32_16x16x32_bf16 v[20:23], v[134:137], v[114:117], v[20:23]
	ds_read_b128 v[114:117], v108 offset:2304
	s_waitcnt lgkmcnt(0)
	v_mfma_f32_16x16x32_bf16 v[52:55], v[110:113], v[114:117], v[52:55]
	v_mfma_f32_16x16x32_bf16 v[56:59], v[118:121], v[114:117], v[56:59]
	v_mfma_f32_16x16x32_bf16 v[60:63], v[122:125], v[114:117], v[60:63]
	v_mfma_f32_16x16x32_bf16 v[48:51], v[134:137], v[114:117], v[48:51]
	ds_read_b128 v[114:117], v108 offset:4608
	s_waitcnt lgkmcnt(0)
	v_mfma_f32_16x16x32_bf16 v[68:71], v[110:113], v[114:117], v[68:71]
	v_mfma_f32_16x16x32_bf16 v[72:75], v[118:121], v[114:117], v[72:75]
	v_mfma_f32_16x16x32_bf16 v[76:79], v[122:125], v[114:117], v[76:79]
	v_mfma_f32_16x16x32_bf16 v[64:67], v[134:137], v[114:117], v[64:67]
	ds_read_b128 v[114:117], v108 offset:6912
	s_waitcnt lgkmcnt(0)
	v_mfma_f32_16x16x32_bf16 v[16:19], v[110:113], v[114:117], v[16:19]
	ds_read_b128 v[110:113], v109 offset:18496
	v_mfma_f32_16x16x32_bf16 v[28:31], v[118:121], v[114:117], v[28:31]
	ds_read_b128 v[118:121], v109 offset:20800
	v_mfma_f32_16x16x32_bf16 v[36:39], v[122:125], v[114:117], v[36:39]
	ds_read_b128 v[122:125], v109 offset:23104
	v_mfma_f32_16x16x32_bf16 v[44:47], v[134:137], v[114:117], v[44:47]
	ds_read_b128 v[134:137], v109 offset:25408
	ds_read_b128 v[114:117], v108 offset:64
	s_waitcnt lgkmcnt(0)
	v_mfma_f32_16x16x32_bf16 v[24:27], v[110:113], v[114:117], v[24:27]
	v_mfma_f32_16x16x32_bf16 v[32:35], v[118:121], v[114:117], v[32:35]
	v_mfma_f32_16x16x32_bf16 v[40:43], v[122:125], v[114:117], v[40:43]
	v_mfma_f32_16x16x32_bf16 v[20:23], v[134:137], v[114:117], v[20:23]
	ds_read_b128 v[114:117], v108 offset:2368
	s_waitcnt lgkmcnt(0)
	v_mfma_f32_16x16x32_bf16 v[52:55], v[110:113], v[114:117], v[52:55]
	v_mfma_f32_16x16x32_bf16 v[56:59], v[118:121], v[114:117], v[56:59]
	v_mfma_f32_16x16x32_bf16 v[60:63], v[122:125], v[114:117], v[60:63]
	v_mfma_f32_16x16x32_bf16 v[48:51], v[134:137], v[114:117], v[48:51]
	ds_read_b128 v[114:117], v108 offset:4672
	s_waitcnt lgkmcnt(0)
	v_mfma_f32_16x16x32_bf16 v[68:71], v[110:113], v[114:117], v[68:71]
	v_mfma_f32_16x16x32_bf16 v[72:75], v[118:121], v[114:117], v[72:75]
	v_mfma_f32_16x16x32_bf16 v[76:79], v[122:125], v[114:117], v[76:79]
	v_mfma_f32_16x16x32_bf16 v[64:67], v[134:137], v[114:117], v[64:67]
	global_load_dwordx4 v[114:117], v[4:5], off offset:1824
	global_load_dwordx4 v[146:149], v[0:1], off offset:1824
	global_load_dwordx4 v[150:153], v[14:15], off offset:256
	v_mfma_f32_16x16x32_bf16 v[16:19], v[110:113], v[138:141], v[16:19]
	global_load_dwordx4 v[110:113], v[12:13], off offset:256
	global_load_dwordx4 v[154:157], v[2:3], off offset:1824
	global_load_dwordx4 v[158:161], v[8:9], off offset:256
	v_mfma_f32_16x16x32_bf16 v[28:31], v[118:121], v[138:141], v[28:31]
	global_load_dwordx4 v[118:121], v[6:7], off offset:256
	s_barrier
	v_mfma_f32_16x16x32_bf16 v[36:39], v[122:125], v[138:141], v[36:39]
	s_waitcnt vmcnt(5)
	ds_write_b128 v104, v[146:149]
	s_waitcnt vmcnt(4)
	ds_write_b128 v104, v[150:153] offset:18432
	ds_write_b128 v105, v[114:117]
	s_waitcnt vmcnt(3)
	ds_write_b128 v105, v[110:113] offset:18432
	s_waitcnt vmcnt(2)
	ds_write_b128 v106, v[154:157]
	s_waitcnt vmcnt(1)
	ds_write_b128 v106, v[158:161] offset:18432
	ds_write_b128 v107, v[142:145]
	s_waitcnt vmcnt(0)
	ds_write_b128 v107, v[118:121] offset:18432
	v_mfma_f32_16x16x32_bf16 v[44:47], v[134:137], v[138:141], v[44:47]
	s_waitcnt lgkmcnt(0)
	s_barrier
	ds_read_b128 v[110:113], v109 offset:18432
	ds_read_b128 v[114:117], v108
	ds_read_b128 v[118:121], v109 offset:20736
	ds_read_b128 v[122:125], v109 offset:23040
	ds_read_b128 v[134:137], v109 offset:25344
	s_waitcnt lgkmcnt(3)
	v_mfma_f32_16x16x32_bf16 v[24:27], v[110:113], v[114:117], v[24:27]
	global_load_dwordx4 v[142:145], v[10:11], off offset:1952
	s_waitcnt lgkmcnt(2)
	v_mfma_f32_16x16x32_bf16 v[32:35], v[118:121], v[114:117], v[32:35]
	s_waitcnt lgkmcnt(1)
	v_mfma_f32_16x16x32_bf16 v[40:43], v[122:125], v[114:117], v[40:43]
	s_waitcnt lgkmcnt(0)
	v_mfma_f32_16x16x32_bf16 v[20:23], v[134:137], v[114:117], v[20:23]
	ds_read_b128 v[114:117], v108 offset:2304
	s_waitcnt lgkmcnt(0)
	v_mfma_f32_16x16x32_bf16 v[52:55], v[110:113], v[114:117], v[52:55]
	v_mfma_f32_16x16x32_bf16 v[56:59], v[118:121], v[114:117], v[56:59]
	v_mfma_f32_16x16x32_bf16 v[60:63], v[122:125], v[114:117], v[60:63]
	v_mfma_f32_16x16x32_bf16 v[48:51], v[134:137], v[114:117], v[48:51]
	ds_read_b128 v[114:117], v108 offset:4608
	s_waitcnt lgkmcnt(0)
	v_mfma_f32_16x16x32_bf16 v[68:71], v[110:113], v[114:117], v[68:71]
	v_mfma_f32_16x16x32_bf16 v[72:75], v[118:121], v[114:117], v[72:75]
	v_mfma_f32_16x16x32_bf16 v[76:79], v[122:125], v[114:117], v[76:79]
	v_mfma_f32_16x16x32_bf16 v[64:67], v[134:137], v[114:117], v[64:67]
	ds_read_b128 v[114:117], v108 offset:6912
	s_waitcnt lgkmcnt(0)
	v_mfma_f32_16x16x32_bf16 v[16:19], v[110:113], v[114:117], v[16:19]
	ds_read_b128 v[110:113], v109 offset:18496
	v_mfma_f32_16x16x32_bf16 v[28:31], v[118:121], v[114:117], v[28:31]
	ds_read_b128 v[118:121], v109 offset:20800
	v_mfma_f32_16x16x32_bf16 v[36:39], v[122:125], v[114:117], v[36:39]
	ds_read_b128 v[122:125], v109 offset:23104
	v_mfma_f32_16x16x32_bf16 v[44:47], v[134:137], v[114:117], v[44:47]
	ds_read_b128 v[134:137], v109 offset:25408
	ds_read_b128 v[114:117], v108 offset:64
	s_waitcnt lgkmcnt(0)
	v_mfma_f32_16x16x32_bf16 v[24:27], v[110:113], v[114:117], v[24:27]
	v_mfma_f32_16x16x32_bf16 v[32:35], v[118:121], v[114:117], v[32:35]
	v_mfma_f32_16x16x32_bf16 v[40:43], v[122:125], v[114:117], v[40:43]
	v_mfma_f32_16x16x32_bf16 v[20:23], v[134:137], v[114:117], v[20:23]
	ds_read_b128 v[114:117], v108 offset:2368
	s_waitcnt lgkmcnt(0)
	v_mfma_f32_16x16x32_bf16 v[52:55], v[110:113], v[114:117], v[52:55]
	v_mfma_f32_16x16x32_bf16 v[56:59], v[118:121], v[114:117], v[56:59]
	v_mfma_f32_16x16x32_bf16 v[60:63], v[122:125], v[114:117], v[60:63]
	v_mfma_f32_16x16x32_bf16 v[48:51], v[134:137], v[114:117], v[48:51]
	ds_read_b128 v[114:117], v108 offset:4672
	s_waitcnt lgkmcnt(0)
	v_mfma_f32_16x16x32_bf16 v[138:141], v[122:125], v[114:117], v[76:79]
	s_nop 2
	ds_read_b128 v[76:79], v108 offset:6976
	v_mfma_f32_16x16x32_bf16 v[68:71], v[110:113], v[114:117], v[68:71]
	v_mfma_f32_16x16x32_bf16 v[72:75], v[118:121], v[114:117], v[72:75]
	v_mfma_f32_16x16x32_bf16 v[64:67], v[134:137], v[114:117], v[64:67]
	global_load_dwordx4 v[114:117], v[4:5], off offset:1952
	global_load_dwordx4 v[146:149], v[0:1], off offset:1952
	global_load_dwordx4 v[150:153], v[14:15], off offset:384
	s_waitcnt lgkmcnt(0)
	v_mfma_f32_16x16x32_bf16 v[14:17], v[110:113], v[76:79], v[16:19]
	global_load_dwordx4 v[10:13], v[12:13], off offset:384
	s_nop 0
	global_load_dwordx4 v[0:3], v[2:3], off offset:1952
	s_nop 0
	global_load_dwordx4 v[110:113], v[8:9], off offset:384
	s_nop 0
	global_load_dwordx4 v[4:7], v[6:7], off offset:384
	s_barrier
	s_waitcnt vmcnt(5)
	ds_write_b128 v104, v[146:149]
	s_waitcnt vmcnt(4)
	ds_write_b128 v104, v[150:153] offset:18432
	ds_write_b128 v105, v[114:117]
	s_waitcnt vmcnt(3)
	ds_write_b128 v105, v[10:13] offset:18432
	s_waitcnt vmcnt(2)
	ds_write_b128 v106, v[0:3]
	s_waitcnt vmcnt(1)
	ds_write_b128 v106, v[110:113] offset:18432
	ds_write_b128 v107, v[142:145]
	s_waitcnt vmcnt(0)
	ds_write_b128 v107, v[4:7] offset:18432
	s_waitcnt lgkmcnt(0)
	s_barrier
	ds_read_b128 v[0:3], v109 offset:18432
	ds_read_b128 v[4:7], v108
	s_waitcnt lgkmcnt(0)
	v_mfma_f32_16x16x32_bf16 v[110:113], v[0:3], v[4:7], v[24:27]
	s_nop 2
	ds_read_b128 v[24:27], v109 offset:20736
	s_waitcnt lgkmcnt(0)
	v_mfma_f32_16x16x32_bf16 v[114:117], v[24:27], v[4:7], v[32:35]
	s_nop 2
	ds_read_b128 v[32:35], v109 offset:23040
	v_mfma_f32_16x16x32_bf16 v[28:31], v[118:121], v[76:79], v[28:31]
	s_waitcnt lgkmcnt(0)
	v_mfma_f32_16x16x32_bf16 v[118:121], v[32:35], v[4:7], v[40:43]
	s_nop 2
	ds_read_b128 v[40:43], v109 offset:25344
	v_mfma_f32_16x16x32_bf16 v[36:39], v[122:125], v[76:79], v[36:39]
	s_waitcnt lgkmcnt(0)
	v_mfma_f32_16x16x32_bf16 v[122:125], v[40:43], v[4:7], v[20:23]
	ds_read_b128 v[4:7], v108 offset:2304
	s_nop 1
	ds_read_b128 v[18:21], v108 offset:6912
	v_mfma_f32_16x16x32_bf16 v[44:47], v[134:137], v[76:79], v[44:47]
	s_waitcnt lgkmcnt(1)
	v_mfma_f32_16x16x32_bf16 v[134:137], v[0:3], v[4:7], v[52:55]
	v_mfma_f32_16x16x32_bf16 v[142:145], v[24:27], v[4:7], v[56:59]
	v_mfma_f32_16x16x32_bf16 v[60:63], v[32:35], v[4:7], v[60:63]
	s_nop 1
	ds_read_b128 v[56:59], v109 offset:25408
	v_mfma_f32_16x16x32_bf16 v[146:149], v[40:43], v[4:7], v[48:51]
	ds_read_b128 v[4:7], v108 offset:4608
	s_waitcnt lgkmcnt(0)
	v_mfma_f32_16x16x32_bf16 v[76:79], v[0:3], v[4:7], v[68:71]
	v_mfma_f32_16x16x32_bf16 v[72:75], v[24:27], v[4:7], v[72:75]
	v_mfma_f32_16x16x32_bf16 v[68:71], v[32:35], v[4:7], v[138:141]
	v_mfma_f32_16x16x32_bf16 v[52:55], v[40:43], v[4:7], v[64:67]
	v_mfma_f32_16x16x32_bf16 v[4:7], v[24:27], v[18:21], v[28:31]
	ds_read_b128 v[24:27], v109 offset:18496
	s_nop 0
	ds_read_b128 v[64:67], v108 offset:2368
	v_mfma_f32_16x16x32_bf16 v[8:11], v[0:3], v[18:21], v[14:17]
	v_mfma_f32_16x16x32_bf16 v[0:3], v[32:35], v[18:21], v[36:39]
	ds_read_b128 v[32:35], v109 offset:20800
	s_nop 1
	ds_read_b128 v[36:39], v108 offset:64
	v_mfma_f32_16x16x32_bf16 v[12:15], v[40:43], v[18:21], v[44:47]
	ds_read_b128 v[40:43], v109 offset:23104
	s_waitcnt lgkmcnt(1)
	v_mfma_f32_16x16x32_bf16 v[16:19], v[24:27], v[36:39], v[110:113]
	s_nop 2
	ds_read_b128 v[110:113], v108 offset:4672
	s_waitcnt lgkmcnt(0)
	v_mfma_f32_16x16x32_bf16 v[76:79], v[24:27], v[110:113], v[76:79]
	s_nop 1
	v_cvt_pk_bf16_f32 v16, v16, v17
	v_cvt_pk_bf16_f32 v17, v18, v19
	v_mfma_f32_16x16x32_bf16 v[72:75], v[32:35], v[110:113], v[72:75]
	v_mfma_f32_16x16x32_bf16 v[68:71], v[40:43], v[110:113], v[68:71]
	v_mfma_f32_16x16x32_bf16 v[52:55], v[56:59], v[110:113], v[52:55]
	ds_read_b128 v[110:113], v108 offset:6976
	v_mfma_f32_16x16x32_bf16 v[20:23], v[32:35], v[36:39], v[114:117]
	s_nop 2
	v_mov_b64_e32 v[114:115], s[84:85]
	v_or_b32_e32 v116, s2, v103
	v_mfma_f32_16x16x32_bf16 v[28:31], v[40:43], v[36:39], v[118:121]
	v_mad_i64_i32 v[100:101], s[2:3], v116, s8, v[114:115]
	v_or_b32_e32 v117, 16, v116
	v_mfma_f32_16x16x32_bf16 v[36:39], v[56:59], v[36:39], v[122:125]
	v_or_b32_e32 v120, 32, v116
	v_mad_i64_i32 v[118:119], s[2:3], v117, s8, v[114:115]
	s_nop 0
	v_or_b32_e32 v122, 48, v116
	v_or_b32_e32 v116, s0, v102
	v_mfma_f32_16x16x32_bf16 v[48:51], v[24:27], v[64:67], v[134:137]
	v_ashrrev_i32_e32 v117, 31, v116
	v_mad_i64_i32 v[120:121], s[2:3], v120, s8, v[114:115]
	v_mfma_f32_16x16x32_bf16 v[44:47], v[32:35], v[64:67], v[142:145]
	v_mad_i64_i32 v[114:115], s[2:3], v122, s8, v[114:115]
	v_cvt_pk_bf16_f32 v18, v20, v21
	v_mfma_f32_16x16x32_bf16 v[60:63], v[40:43], v[64:67], v[60:63]
	v_cvt_pk_bf16_f32 v19, v22, v23
	v_cvt_pk_bf16_f32 v20, v28, v29
	v_cvt_pk_bf16_f32 v21, v30, v31
	v_mfma_f32_16x16x32_bf16 v[64:67], v[56:59], v[64:67], v[146:149]
	v_cvt_pk_bf16_f32 v22, v36, v37
	v_cvt_pk_bf16_f32 v23, v38, v39
	v_cvt_pk_bf16_f32 v28, v48, v49
	s_waitcnt lgkmcnt(0)
	v_mfma_f32_16x16x32_bf16 v[8:11], v[24:27], v[110:113], v[8:11]
	v_lshlrev_b64 v[24:25], 1, v[116:117]
	v_lshl_add_u64 v[26:27], v[100:101], 0, v[24:25]
	v_lshl_add_u64 v[100:101], v[118:119], 0, v[24:25]
	v_mfma_f32_16x16x32_bf16 v[4:7], v[32:35], v[110:113], v[4:7]
	v_lshl_add_u64 v[32:33], v[120:121], 0, v[24:25]
	v_lshl_add_u64 v[24:25], v[114:115], 0, v[24:25]
	v_lshl_add_u64 v[26:27], v[26:27], 0, v[128:129]
	v_mfma_f32_16x16x32_bf16 v[0:3], v[40:43], v[110:113], v[0:3]
	v_lshl_add_u64 v[34:35], v[100:101], 0, v[128:129]
	v_lshl_add_u64 v[32:33], v[32:33], 0, v[128:129]
	v_lshl_add_u64 v[24:25], v[24:25], 0, v[128:129]
	v_mfma_f32_16x16x32_bf16 v[12:15], v[56:59], v[110:113], v[12:15]
	v_cvt_pk_bf16_f32 v29, v50, v51
	v_cvt_pk_bf16_f32 v30, v44, v45
	v_cvt_pk_bf16_f32 v31, v46, v47
	v_cvt_pk_bf16_f32 v36, v60, v61
	v_cvt_pk_bf16_f32 v37, v62, v63
	v_cvt_pk_bf16_f32 v38, v64, v65
	v_cvt_pk_bf16_f32 v39, v66, v67
	v_cvt_pk_bf16_f32 v40, v76, v77
	v_cvt_pk_bf16_f32 v41, v78, v79
	v_cvt_pk_bf16_f32 v42, v72, v73
	v_cvt_pk_bf16_f32 v43, v74, v75
	v_cvt_pk_bf16_f32 v44, v68, v69
	v_cvt_pk_bf16_f32 v45, v70, v71
	v_cvt_pk_bf16_f32 v46, v52, v53
	v_cvt_pk_bf16_f32 v47, v54, v55
	v_cvt_pk_bf16_f32 v8, v8, v9
	v_cvt_pk_bf16_f32 v9, v10, v11
	v_cvt_pk_bf16_f32 v10, v4, v5
	v_cvt_pk_bf16_f32 v11, v6, v7
	v_cvt_pk_bf16_f32 v0, v0, v1
	v_cvt_pk_bf16_f32 v1, v2, v3
	v_cvt_pk_bf16_f32 v2, v12, v13
	v_cvt_pk_bf16_f32 v3, v14, v15
	v_bfe_u32 v248, v131, 4, 1
	v_mul_u32_u24_e32 v248, 24, v248
	v_mov_b32_e32 v249, 0
	v_lshl_add_u64 v[240:241], v[26:27], 0, v[248:249]
	v_lshl_add_u64 v[242:243], v[34:35], 0, v[248:249]
	v_lshl_add_u64 v[244:245], v[32:33], 0, v[248:249]
	v_lshl_add_u64 v[246:247], v[24:25], 0, v[248:249]
	v_permlane16_swap_b32 v16, v18
	v_permlane16_swap_b32 v17, v19
	v_permlane16_swap_b32 v20, v22
	v_permlane16_swap_b32 v21, v23
	v_permlane16_swap_b32 v28, v30
	v_permlane16_swap_b32 v29, v31
	v_permlane16_swap_b32 v36, v38
	v_permlane16_swap_b32 v37, v39
	v_permlane16_swap_b32 v40, v42
	v_permlane16_swap_b32 v41, v43
	v_permlane16_swap_b32 v44, v46
	v_permlane16_swap_b32 v45, v47
	v_permlane16_swap_b32 v8, v10
	v_permlane16_swap_b32 v9, v11
	v_permlane16_swap_b32 v0, v2
	v_permlane16_swap_b32 v1, v3
	global_store_dwordx4 v[240:241], v[16:19], off
	global_store_dwordx4 v[240:241], v[20:23], off offset:64
	global_store_dwordx4 v[242:243], v[28:31], off
	global_store_dwordx4 v[242:243], v[36:39], off offset:64
	global_store_dwordx4 v[244:245], v[40:43], off
	global_store_dwordx4 v[244:245], v[44:47], off offset:64
	global_store_dwordx4 v[246:247], v[8:11], off
	global_store_dwordx4 v[246:247], v[0:3], off offset:64
	s_add_i32 s4, s1, s4
	s_cmpk_lt_i32 s4, 0x330
	s_cbranch_scc1 .LBB0_1296

.LBB0_1300:
	s_ashr_i32 s0, s10, 31
	s_lshr_b32 s0, s0, 30
	s_add_i32 s0, s10, s0
	s_ashr_i32 s11, s0, 2
	s_lshl_b32 s0, s11, 7
	s_ashr_i32 s1, s0, 31
	s_lshl_b64 s[6:7], s[0:1], 12
	s_lshl_b32 s1, s11, 9
	s_lshl_b32 s4, s10, 7
	s_sub_i32 s4, s4, s1
	s_ashr_i32 s5, s4, 31
	s_lshl_b64 s[12:13], s[4:5], 8
	s_add_u32 s8, s82, s6
	s_addc_u32 s9, s83, s7
	v_lshl_add_u64 v[54:55], s[8:9], 0, v[128:129]
	v_readlane_b32 s6, v252, 37
	s_waitcnt lgkmcnt(0)
	v_lshl_add_u64 v[18:19], v[54:55], 0, v[0:1]
	v_readlane_b32 s7, v252, 38
	s_add_u32 s6, s6, s12
	global_load_dwordx4 v[18:21], v[18:19], off offset:2080
	v_lshl_add_u64 v[42:43], v[54:55], 0, v[4:5]
	s_addc_u32 s7, s7, s13
	global_load_dwordx4 v[42:45], v[42:43], off offset:2080
	v_lshl_add_u64 v[50:51], v[54:55], 0, v[8:9]
	v_lshl_add_u64 v[62:63], s[6:7], 0, v[128:129]
	global_load_dwordx4 v[50:53], v[50:51], off offset:2080
	v_lshl_add_u64 v[54:55], v[54:55], 0, v[12:13]
	v_lshl_add_u64 v[38:39], v[62:63], 0, v[2:3]
	global_load_dwordx4 v[54:57], v[54:55], off offset:2080
	v_lshl_add_u64 v[46:47], v[62:63], 0, v[6:7]
	global_load_dwordx4 v[38:41], v[38:39], off
	v_lshl_add_u64 v[58:59], v[62:63], 0, v[10:11]
	global_load_dwordx4 v[46:49], v[46:47], off
	v_lshl_add_u64 v[62:63], v[62:63], 0, v[14:15]
	global_load_dwordx4 v[58:61], v[58:59], off
	v_lshl_add_u64 v[126:127], s[8:9], 0, v[12:13]
	global_load_dwordx4 v[62:65], v[62:63], off
	s_barrier
	v_lshl_add_u64 v[142:143], s[8:9], 0, v[0:1]
	v_lshl_add_u64 v[126:127], v[126:127], 0, v[128:129]
	v_lshl_add_u64 v[144:145], s[6:7], 0, v[2:3]
	v_lshl_add_u64 v[144:145], v[144:145], 0, v[128:129]
	v_or_b32_e32 v37, s0, v23
	v_mov_b32_e32 v17, v129
	s_waitcnt vmcnt(7)
	ds_write_b128 v31, v[18:21]
	s_waitcnt vmcnt(6)
	ds_write_b128 v32, v[42:45]
	s_waitcnt vmcnt(5)
	ds_write_b128 v33, v[50:53]
	s_waitcnt vmcnt(4)
	ds_write_b128 v34, v[54:57]
	s_waitcnt vmcnt(3)
	ds_write_b128 v31, v[38:41] offset:18432
	s_waitcnt vmcnt(2)
	ds_write_b128 v32, v[46:49] offset:18432
	s_waitcnt vmcnt(1)
	ds_write_b128 v33, v[58:61] offset:18432
	s_waitcnt vmcnt(0)
	ds_write_b128 v34, v[62:65] offset:18432
	s_waitcnt lgkmcnt(0)
	s_barrier
	ds_read_b128 v[18:21], v36 offset:18432
	ds_read_b128 v[38:41], v35
	ds_read_b128 v[42:45], v35 offset:64
	ds_read_b128 v[46:49], v36 offset:18496
	ds_read_b128 v[54:57], v36 offset:20736
	ds_read_b128 v[58:61], v36 offset:20800
	ds_read_b128 v[66:69], v36 offset:23040
	ds_read_b128 v[70:73], v36 offset:23104
	ds_read_b128 v[78:81], v36 offset:25344
	ds_read_b128 v[82:85], v36 offset:25408
	ds_read_b128 v[86:89], v35 offset:2304
	ds_read_b128 v[90:93], v35 offset:2368
	ds_read_b128 v[106:109], v35 offset:4608
	ds_read_b128 v[110:113], v35 offset:4672
	ds_read_b128 v[134:137], v35 offset:6912
	ds_read_b128 v[138:141], v35 offset:6976
	s_waitcnt lgkmcnt(14)
	v_mfma_f32_16x16x32_bf16 v[50:53], v[18:21], v[38:41], 0
	s_waitcnt lgkmcnt(11)
	v_mfma_f32_16x16x32_bf16 v[62:65], v[54:57], v[38:41], 0
	s_waitcnt lgkmcnt(9)
	v_mfma_f32_16x16x32_bf16 v[74:77], v[66:69], v[38:41], 0
	s_waitcnt lgkmcnt(7)
	v_mfma_f32_16x16x32_bf16 v[38:41], v[78:81], v[38:41], 0
	s_waitcnt lgkmcnt(5)
	v_mfma_f32_16x16x32_bf16 v[94:97], v[18:21], v[86:89], 0
	v_mfma_f32_16x16x32_bf16 v[98:101], v[54:57], v[86:89], 0
	v_mfma_f32_16x16x32_bf16 v[102:105], v[66:69], v[86:89], 0
	v_mfma_f32_16x16x32_bf16 v[86:89], v[78:81], v[86:89], 0
	s_waitcnt lgkmcnt(3)
	v_mfma_f32_16x16x32_bf16 v[114:117], v[18:21], v[106:109], 0
	v_mfma_f32_16x16x32_bf16 v[118:121], v[54:57], v[106:109], 0
	v_mfma_f32_16x16x32_bf16 v[122:125], v[66:69], v[106:109], 0
	v_mfma_f32_16x16x32_bf16 v[106:109], v[78:81], v[106:109], 0
	s_waitcnt lgkmcnt(1)
	v_mfma_f32_16x16x32_bf16 v[18:21], v[18:21], v[134:137], 0
	v_mfma_f32_16x16x32_bf16 v[54:57], v[54:57], v[134:137], 0
	v_mfma_f32_16x16x32_bf16 v[66:69], v[66:69], v[134:137], 0
	v_mfma_f32_16x16x32_bf16 v[78:81], v[78:81], v[134:137], 0
	v_lshl_add_u64 v[134:135], s[8:9], 0, v[8:9]
	v_lshl_add_u64 v[136:137], s[8:9], 0, v[4:5]
	v_lshl_add_u64 v[146:147], v[134:135], 0, v[128:129]
	v_mfma_f32_16x16x32_bf16 v[50:53], v[46:49], v[42:45], v[50:53]
	v_lshl_add_u64 v[134:135], v[136:137], 0, v[128:129]
	v_lshl_add_u64 v[136:137], s[6:7], 0, v[6:7]
	v_lshl_add_u64 v[148:149], v[136:137], 0, v[128:129]
	v_mfma_f32_16x16x32_bf16 v[62:65], v[58:61], v[42:45], v[62:65]
	v_mfma_f32_16x16x32_bf16 v[74:77], v[70:73], v[42:45], v[74:77]
	v_mfma_f32_16x16x32_bf16 v[38:41], v[82:85], v[42:45], v[38:41]
	v_mfma_f32_16x16x32_bf16 v[42:45], v[46:49], v[90:93], v[94:97]
	v_mfma_f32_16x16x32_bf16 v[94:97], v[58:61], v[90:93], v[98:101]
	v_mfma_f32_16x16x32_bf16 v[98:101], v[70:73], v[90:93], v[102:105]
	s_nop 2
	v_lshl_add_u64 v[102:103], s[6:7], 0, v[14:15]
	v_lshl_add_u64 v[104:105], s[6:7], 0, v[10:11]
	v_mfma_f32_16x16x32_bf16 v[86:89], v[82:85], v[90:93], v[86:89]
	v_lshl_add_u64 v[154:155], v[102:103], 0, v[128:129]
	v_lshl_add_u64 v[150:151], v[104:105], 0, v[128:129]
	v_mfma_f32_16x16x32_bf16 v[90:93], v[46:49], v[110:113], v[114:117]
	v_mfma_f32_16x16x32_bf16 v[102:105], v[58:61], v[110:113], v[118:121]
	s_nop 1
	global_load_dwordx4 v[114:117], v[126:127], off offset:2208
	global_load_dwordx4 v[118:121], v[134:135], off offset:2208
	v_lshl_add_u64 v[126:127], v[142:143], 0, v[128:129]
	global_load_dwordx4 v[134:137], v[126:127], off offset:2208
	s_nop 0
	global_load_dwordx4 v[142:145], v[144:145], off offset:128
	v_mfma_f32_16x16x32_bf16 v[122:125], v[70:73], v[110:113], v[122:125]
	v_mfma_f32_16x16x32_bf16 v[106:109], v[82:85], v[110:113], v[106:109]
	global_load_dwordx4 v[110:113], v[148:149], off offset:128
	s_nop 0
	global_load_dwordx4 v[146:149], v[146:147], off offset:2208
	s_nop 0
	global_load_dwordx4 v[150:153], v[150:151], off offset:128
	s_waitcnt lgkmcnt(0)
	v_mfma_f32_16x16x32_bf16 v[18:21], v[46:49], v[138:141], v[18:21]
	global_load_dwordx4 v[46:49], v[154:155], off offset:128
	s_barrier
	s_waitcnt vmcnt(5)
	ds_write_b128 v31, v[134:137]
	s_waitcnt vmcnt(4)
	ds_write_b128 v31, v[142:145] offset:18432
	ds_write_b128 v32, v[118:121]
	s_waitcnt vmcnt(3)
	ds_write_b128 v32, v[110:113] offset:18432
	s_waitcnt vmcnt(2)
	ds_write_b128 v33, v[146:149]
	s_waitcnt vmcnt(1)
	ds_write_b128 v33, v[150:153] offset:18432
	ds_write_b128 v34, v[114:117]
	s_waitcnt vmcnt(0)
	ds_write_b128 v34, v[46:49] offset:18432
	s_waitcnt lgkmcnt(0)
	s_barrier
	ds_read_b128 v[46:49], v36 offset:18432
	v_mfma_f32_16x16x32_bf16 v[54:57], v[58:61], v[138:141], v[54:57]
	v_mfma_f32_16x16x32_bf16 v[58:61], v[70:73], v[138:141], v[66:69]
	v_mfma_f32_16x16x32_bf16 v[66:69], v[82:85], v[138:141], v[78:81]
	ds_read_b128 v[70:73], v35
	s_nop 1
	ds_read_b128 v[78:81], v35 offset:64
	ds_read_b128 v[82:85], v36 offset:18496
	ds_read_b128 v[110:113], v36 offset:20736
	ds_read_b128 v[114:117], v36 offset:20800
	ds_read_b128 v[118:121], v36 offset:23040
	ds_read_b128 v[134:137], v36 offset:23104
	ds_read_b128 v[138:141], v36 offset:25344
	ds_read_b128 v[142:145], v36 offset:25408
	s_waitcnt lgkmcnt(8)
	v_mfma_f32_16x16x32_bf16 v[50:53], v[46:49], v[70:73], v[50:53]
	s_waitcnt lgkmcnt(5)
	v_mfma_f32_16x16x32_bf16 v[62:65], v[110:113], v[70:73], v[62:65]
	s_waitcnt lgkmcnt(3)
	v_mfma_f32_16x16x32_bf16 v[74:77], v[118:121], v[70:73], v[74:77]
	s_waitcnt lgkmcnt(1)
	v_mfma_f32_16x16x32_bf16 v[38:41], v[138:141], v[70:73], v[38:41]
	ds_read_b128 v[70:73], v35 offset:2304
	ds_read_b128 v[146:149], v35 offset:2368
	s_waitcnt lgkmcnt(1)
	v_mfma_f32_16x16x32_bf16 v[42:45], v[46:49], v[70:73], v[42:45]
	v_mfma_f32_16x16x32_bf16 v[94:97], v[110:113], v[70:73], v[94:97]
	v_mfma_f32_16x16x32_bf16 v[98:101], v[118:121], v[70:73], v[98:101]
	v_mfma_f32_16x16x32_bf16 v[70:73], v[138:141], v[70:73], v[86:89]
	s_nop 2
	ds_read_b128 v[86:89], v35 offset:4608
	ds_read_b128 v[150:153], v35 offset:4672
	ds_read_b128 v[154:157], v35 offset:6912
	s_waitcnt lgkmcnt(2)
	v_mfma_f32_16x16x32_bf16 v[90:93], v[46:49], v[86:89], v[90:93]
	v_mfma_f32_16x16x32_bf16 v[102:105], v[110:113], v[86:89], v[102:105]
	v_mfma_f32_16x16x32_bf16 v[122:125], v[118:121], v[86:89], v[122:125]
	v_mfma_f32_16x16x32_bf16 v[86:89], v[138:141], v[86:89], v[106:109]
	s_nop 2
	ds_read_b128 v[106:109], v35 offset:6976
	s_waitcnt lgkmcnt(1)
	v_mfma_f32_16x16x32_bf16 v[46:49], v[46:49], v[154:157], v[18:21]
	s_nop 2
	v_or_b32_e32 v20, v37, v22
	v_or_b32_e32 v18, s4, v24
	v_mfma_f32_16x16x32_bf16 v[50:53], v[82:85], v[78:81], v[50:53]
	v_ashrrev_i32_e32 v21, 31, v20
	v_ashrrev_i32_e32 v19, 31, v18
	v_lshlrev_b64 v[126:127], 10, v[20:21]
	v_lshlrev_b64 v[18:19], 1, v[18:19]
	v_lshl_add_u64 v[126:127], s[86:87], 0, v[126:127]
	v_mfma_f32_16x16x32_bf16 v[62:65], v[114:117], v[78:81], v[62:65]
	v_lshl_add_u64 v[126:127], v[126:127], 0, v[18:19]
	v_lshl_add_u64 v[126:127], v[126:127], 0, v[16:17]
	v_cvt_pk_bf16_f32 v50, v50, v51
	v_cvt_pk_bf16_f32 v51, v52, v53
	v_bfe_u32 v248, v131, 4, 1
	v_mul_u32_u24_e32 v248, 24, v248
	v_mov_b32_e32 v249, 0
	v_mov_b32_e32 v208, v50
	v_mov_b32_e32 v209, v51
	v_lshlrev_b32_e32 v21, 16, v50
	v_and_b32_e32 v50, 0xffff0000, v50
	v_mul_f32_e32 v133, v50, v50
	v_mfma_f32_16x16x32_bf16 v[74:77], v[134:137], v[78:81], v[74:77]
	v_cvt_pk_bf16_f32 v158, v62, v63
	v_lshlrev_b32_e32 v62, 16, v51
	v_fmac_f32_e32 v133, v21, v21
	v_and_b32_e32 v63, 0xffff0000, v51
	v_fmac_f32_e32 v133, v62, v62
	v_cvt_pk_bf16_f32 v159, v64, v65
	v_lshlrev_b32_e32 v64, 16, v158
	v_fmac_f32_e32 v133, v63, v63
	v_and_b32_e32 v65, 0xffff0000, v158
	v_fmac_f32_e32 v133, v64, v64
	v_cvt_pk_bf16_f32 v160, v74, v75
	v_lshlrev_b32_e32 v74, 16, v159
	v_fmac_f32_e32 v133, v65, v65
	v_and_b32_e32 v75, 0xffff0000, v159
	v_fmac_f32_e32 v133, v74, v74
	v_mfma_f32_16x16x32_bf16 v[38:41], v[142:145], v[78:81], v[38:41]
	v_fmac_f32_e32 v133, v75, v75
	v_lshlrev_b32_e32 v21, 16, v160
	v_cvt_pk_bf16_f32 v161, v76, v77
	v_fmac_f32_e32 v133, v21, v21
	v_and_b32_e32 v21, 0xffff0000, v160
	v_mfma_f32_16x16x32_bf16 v[42:45], v[82:85], v[146:149], v[42:45]
	v_fmac_f32_e32 v133, v21, v21
	v_lshlrev_b32_e32 v21, 16, v161
	v_fmac_f32_e32 v133, v21, v21
	v_mfma_f32_16x16x32_bf16 v[50:53], v[110:113], v[154:157], v[54:57]
	v_and_b32_e32 v21, 0xffff0000, v161
	v_cvt_pk_bf16_f32 v38, v38, v39
	v_fmac_f32_e32 v133, v21, v21
	v_lshlrev_b32_e32 v21, 16, v38
	v_mfma_f32_16x16x32_bf16 v[54:57], v[118:121], v[154:157], v[58:61]
	v_cvt_pk_bf16_f32 v39, v40, v41
	v_fmac_f32_e32 v133, v21, v21
	v_and_b32_e32 v21, 0xffff0000, v38
	v_mfma_f32_16x16x32_bf16 v[58:61], v[138:141], v[154:157], v[66:69]
	v_cvt_pk_bf16_f32 v42, v42, v43
	v_fmac_f32_e32 v133, v21, v21
	v_lshlrev_b32_e32 v21, 16, v39
	v_mfma_f32_16x16x32_bf16 v[62:65], v[114:117], v[146:149], v[94:97]
	v_cvt_pk_bf16_f32 v43, v44, v45
	v_fmac_f32_e32 v133, v21, v21
	v_and_b32_e32 v21, 0xffff0000, v39
	s_waitcnt lgkmcnt(0)
	v_mfma_f32_16x16x32_bf16 v[44:47], v[82:85], v[106:109], v[46:49]
	v_mov_b32_e32 v210, v158
	v_mov_b32_e32 v211, v159
	v_lshl_add_u64 v[240:241], v[126:127], 0, v[248:249]
	s_nop 0
	v_permlane16_swap_b32 v208, v210
	v_permlane16_swap_b32 v209, v211
	global_store_dwordx4 v[240:241], v[208:211], off
	v_mov_b32_e32 v212, v160
	v_mov_b32_e32 v213, v161
	v_mov_b32_e32 v214, v38
	v_mov_b32_e32 v215, v39
	v_lshl_add_u64 v[242:243], v[126:127], 0, v[248:249]
	s_nop 0
	v_permlane16_swap_b32 v212, v214
	v_permlane16_swap_b32 v213, v215
	global_store_dwordx4 v[242:243], v[212:215], off offset:64
	v_lshlrev_b32_e32 v39, 16, v42
	v_mfma_f32_16x16x32_bf16 v[48:51], v[114:117], v[106:109], v[50:53]
	v_or_b32_e32 v40, 16, v20
	v_ashrrev_i32_e32 v41, 31, v40
	v_lshlrev_b64 v[40:41], 10, v[40:41]
	v_and_b32_e32 v52, 0xffff0000, v42
	v_mfma_f32_16x16x32_bf16 v[74:77], v[82:85], v[150:153], v[90:93]
	v_mul_f32_e32 v82, v52, v52
	v_fmac_f32_e32 v82, v39, v39
	v_lshlrev_b32_e32 v39, 16, v43
	v_mfma_f32_16x16x32_bf16 v[66:69], v[134:137], v[146:149], v[98:101]
	v_fmac_f32_e32 v82, v39, v39
	v_and_b32_e32 v39, 0xffff0000, v43
	v_fmac_f32_e32 v82, v39, v39
	v_mfma_f32_16x16x32_bf16 v[52:55], v[134:137], v[106:109], v[54:57]
	v_lshl_add_u64 v[40:41], s[86:87], 0, v[40:41]
	v_lshl_add_u64 v[40:41], v[40:41], 0, v[18:19]
	v_lshl_add_u64 v[40:41], v[40:41], 0, v[16:17]
	v_mfma_f32_16x16x32_bf16 v[56:59], v[142:145], v[106:109], v[58:61]
	v_cvt_pk_bf16_f32 v44, v44, v45
	v_cvt_pk_bf16_f32 v45, v46, v47
	v_cvt_pk_bf16_f32 v46, v48, v49
	v_cvt_pk_bf16_f32 v60, v62, v63
	v_lshlrev_b32_e32 v39, 16, v60
	v_mfma_f32_16x16x32_bf16 v[70:73], v[142:145], v[146:149], v[70:73]
	v_cvt_pk_bf16_f32 v61, v64, v65
	v_fmac_f32_e32 v82, v39, v39
	v_and_b32_e32 v39, 0xffff0000, v60
	v_fmac_f32_e32 v82, v39, v39
	v_lshlrev_b32_e32 v39, 16, v61
	v_fmac_f32_e32 v82, v39, v39
	v_and_b32_e32 v39, 0xffff0000, v61
	v_cvt_pk_bf16_f32 v62, v66, v67
	v_fmac_f32_e32 v82, v39, v39
	v_lshlrev_b32_e32 v39, 16, v62
	v_cvt_pk_bf16_f32 v63, v68, v69
	v_fmac_f32_e32 v82, v39, v39
	v_and_b32_e32 v39, 0xffff0000, v62
	v_cvt_pk_bf16_f32 v64, v70, v71
	v_cvt_pk_bf16_f32 v65, v72, v73
	v_mov_b32_e32 v216, v42
	v_mov_b32_e32 v217, v43
	v_mov_b32_e32 v218, v60
	v_mov_b32_e32 v219, v61
	v_lshl_add_u64 v[244:245], v[40:41], 0, v[248:249]
	s_nop 0
	v_permlane16_swap_b32 v216, v218
	v_permlane16_swap_b32 v217, v219
	global_store_dwordx4 v[244:245], v[216:219], off
	v_mov_b32_e32 v220, v62
	v_mov_b32_e32 v221, v63
	v_mov_b32_e32 v222, v64
	v_mov_b32_e32 v223, v65
	v_lshl_add_u64 v[246:247], v[40:41], 0, v[248:249]
	s_nop 0
	v_permlane16_swap_b32 v220, v222
	v_permlane16_swap_b32 v221, v223
	global_store_dwordx4 v[246:247], v[220:223], off offset:64
	v_or_b32_e32 v42, 32, v20
	v_fmac_f32_e32 v82, v39, v39
	v_lshlrev_b32_e32 v39, 16, v63
	v_ashrrev_i32_e32 v43, 31, v42
	v_mfma_f32_16x16x32_bf16 v[78:81], v[114:117], v[150:153], v[102:105]
	v_fmac_f32_e32 v82, v39, v39
	v_and_b32_e32 v39, 0xffff0000, v63
	v_lshlrev_b64 v[42:43], 10, v[42:43]
	v_mfma_f32_16x16x32_bf16 v[90:93], v[134:137], v[150:153], v[122:125]
	v_fmac_f32_e32 v82, v39, v39
	v_lshlrev_b32_e32 v39, 16, v64
	v_lshl_add_u64 v[42:43], s[86:87], 0, v[42:43]
	v_mfma_f32_16x16x32_bf16 v[86:89], v[142:145], v[150:153], v[86:89]
	v_fmac_f32_e32 v82, v39, v39
	v_and_b32_e32 v39, 0xffff0000, v64
	v_cvt_pk_bf16_f32 v60, v74, v75
	v_lshl_add_u64 v[42:43], v[42:43], 0, v[18:19]
	v_fmac_f32_e32 v82, v39, v39
	v_lshlrev_b32_e32 v39, 16, v65
	v_cvt_pk_bf16_f32 v61, v76, v77
	v_lshl_add_u64 v[42:43], v[42:43], 0, v[16:17]
	v_and_b32_e32 v62, 0xffff0000, v60
	v_fmac_f32_e32 v82, v39, v39
	v_and_b32_e32 v39, 0xffff0000, v65
	v_mul_f32_e32 v68, v62, v62
	v_cvt_pk_bf16_f32 v62, v78, v79
	v_cvt_pk_bf16_f32 v63, v80, v81
	v_cvt_pk_bf16_f32 v64, v90, v91
	v_cvt_pk_bf16_f32 v65, v92, v93
	v_cvt_pk_bf16_f32 v66, v86, v87
	v_cvt_pk_bf16_f32 v67, v88, v89
	v_mov_b32_e32 v224, v60
	v_mov_b32_e32 v225, v61
	v_mov_b32_e32 v226, v62
	v_mov_b32_e32 v227, v63
	v_lshl_add_u64 v[240:241], v[42:43], 0, v[248:249]
	s_nop 0
	v_permlane16_swap_b32 v224, v226
	v_permlane16_swap_b32 v225, v227
	global_store_dwordx4 v[240:241], v[224:227], off
	v_mov_b32_e32 v228, v64
	v_mov_b32_e32 v229, v65
	v_mov_b32_e32 v230, v66
	v_mov_b32_e32 v231, v67
	v_lshl_add_u64 v[242:243], v[42:43], 0, v[248:249]
	s_nop 0
	v_permlane16_swap_b32 v228, v230
	v_permlane16_swap_b32 v229, v231
	global_store_dwordx4 v[242:243], v[228:231], off offset:64
	v_and_b32_e32 v43, 0xffff0000, v44
	v_lshlrev_b32_e32 v41, 16, v60
	v_or_b32_e32 v60, 48, v20
	v_lshlrev_b32_e32 v20, 16, v44
	v_mul_f32_e32 v43, v43, v43
	v_fmac_f32_e32 v68, v41, v41
	v_lshlrev_b32_e32 v41, 16, v61
	v_fmac_f32_e32 v43, v20, v20
	v_lshlrev_b32_e32 v20, 16, v45
	v_fmac_f32_e32 v68, v41, v41
	v_and_b32_e32 v41, 0xffff0000, v61
	v_fmac_f32_e32 v43, v20, v20
	v_and_b32_e32 v20, 0xffff0000, v45
	v_fmac_f32_e32 v68, v41, v41
	v_lshlrev_b32_e32 v41, 16, v62
	v_fmac_f32_e32 v43, v20, v20
	v_lshlrev_b32_e32 v20, 16, v46
	v_fmac_f32_e32 v68, v41, v41
	v_and_b32_e32 v41, 0xffff0000, v62
	v_cvt_pk_bf16_f32 v47, v50, v51
	v_fmac_f32_e32 v43, v20, v20
	v_and_b32_e32 v20, 0xffff0000, v46
	v_fmac_f32_e32 v68, v41, v41
	v_lshlrev_b32_e32 v41, 16, v63
	v_fmac_f32_e32 v43, v20, v20
	v_lshlrev_b32_e32 v20, 16, v47
	v_fmac_f32_e32 v68, v41, v41
	v_and_b32_e32 v41, 0xffff0000, v63
	v_fmac_f32_e32 v43, v20, v20
	v_and_b32_e32 v20, 0xffff0000, v47
	v_cvt_pk_bf16_f32 v48, v52, v53
	v_fmac_f32_e32 v68, v41, v41
	v_lshlrev_b32_e32 v41, 16, v64
	v_fmac_f32_e32 v43, v20, v20
	v_lshlrev_b32_e32 v20, 16, v48
	v_fmac_f32_e32 v68, v41, v41
	v_and_b32_e32 v41, 0xffff0000, v64
	v_cvt_pk_bf16_f32 v49, v54, v55
	v_fmac_f32_e32 v43, v20, v20
	v_and_b32_e32 v20, 0xffff0000, v48
	v_fmac_f32_e32 v68, v41, v41
	v_lshlrev_b32_e32 v41, 16, v65
	v_fmac_f32_e32 v43, v20, v20
	v_lshlrev_b32_e32 v20, 16, v49
	v_fmac_f32_e32 v68, v41, v41
	v_and_b32_e32 v41, 0xffff0000, v65
	v_fmac_f32_e32 v43, v20, v20
	v_and_b32_e32 v20, 0xffff0000, v49
	v_cvt_pk_bf16_f32 v50, v56, v57
	v_fmac_f32_e32 v68, v41, v41
	v_lshlrev_b32_e32 v41, 16, v66
	v_fmac_f32_e32 v43, v20, v20
	v_lshlrev_b32_e32 v20, 16, v50
	v_fmac_f32_e32 v68, v41, v41
	v_and_b32_e32 v41, 0xffff0000, v66
	v_cvt_pk_bf16_f32 v51, v58, v59
	v_fmac_f32_e32 v43, v20, v20
	v_and_b32_e32 v20, 0xffff0000, v50
	v_fmac_f32_e32 v68, v41, v41
	v_lshlrev_b32_e32 v41, 16, v67
	v_fmac_f32_e32 v43, v20, v20
	v_lshlrev_b32_e32 v20, 16, v51
	v_fmac_f32_e32 v68, v41, v41
	v_and_b32_e32 v41, 0xffff0000, v67
	v_fmac_f32_e32 v43, v20, v20
	v_and_b32_e32 v20, 0xffff0000, v51
	v_fmac_f32_e32 v133, v21, v21
	v_fmac_f32_e32 v82, v39, v39
	v_fmac_f32_e32 v68, v41, v41
	v_fmac_f32_e32 v43, v20, v20
	ds_bpermute_b32 v21, v25, v133
	ds_bpermute_b32 v39, v25, v82
	ds_bpermute_b32 v41, v25, v68
	ds_bpermute_b32 v20, v25, v43
	v_ashrrev_i32_e32 v61, 31, v60
	v_lshlrev_b64 v[52:53], 10, v[60:61]
	v_lshl_add_u64 v[52:53], s[86:87], 0, v[52:53]
	v_lshl_add_u64 v[18:19], v[52:53], 0, v[18:19]
	s_waitcnt lgkmcnt(3)
	v_add_f32_e32 v21, v133, v21
	s_waitcnt lgkmcnt(2)
	v_add_f32_e32 v39, v82, v39
	s_waitcnt lgkmcnt(1)
	v_add_f32_e32 v41, v68, v41
	v_lshl_add_u64 v[52:53], v[18:19], 0, v[16:17]
	s_waitcnt lgkmcnt(0)
	v_add_f32_e32 v17, v43, v20
	ds_bpermute_b32 v38, v26, v21
	ds_bpermute_b32 v40, v26, v39
	ds_bpermute_b32 v42, v26, v41
	ds_bpermute_b32 v18, v26, v17
	v_mov_b32_e32 v232, v44
	v_mov_b32_e32 v233, v45
	v_mov_b32_e32 v234, v46
	v_mov_b32_e32 v235, v47
	v_lshl_add_u64 v[244:245], v[52:53], 0, v[248:249]
	s_nop 0
	v_permlane16_swap_b32 v232, v234
	v_permlane16_swap_b32 v233, v235
	global_store_dwordx4 v[244:245], v[232:235], off
	v_mov_b32_e32 v236, v48
	v_mov_b32_e32 v237, v49
	v_mov_b32_e32 v238, v50
	v_mov_b32_e32 v239, v51
	v_lshl_add_u64 v[246:247], v[52:53], 0, v[248:249]
	s_nop 0
	v_permlane16_swap_b32 v236, v238
	v_permlane16_swap_b32 v237, v239
	global_store_dwordx4 v[246:247], v[236:239], off offset:64
	s_and_saveexec_b64 s[6:7], vcc
	s_cbranch_execz .LBB0_1299
	s_waitcnt lgkmcnt(3)
	v_add_f32_e32 v19, v21, v38
	s_waitcnt lgkmcnt(2)
	v_add_f32_e32 v20, v39, v40
	v_max3_f32 v19, v19, 0, v20
	s_waitcnt lgkmcnt(1)
	v_add_f32_e32 v20, v41, v42
	s_waitcnt lgkmcnt(0)
	v_add_f32_e32 v17, v17, v18
	v_max3_f32 v17, v19, v20, v17
	ds_bpermute_b32 v18, v27, v17
	s_waitcnt lgkmcnt(0)
	v_max_f32_e32 v18, v18, v18
	v_max_f32_e32 v17, v17, v18
	ds_bpermute_b32 v18, v28, v17
	s_waitcnt lgkmcnt(0)
	v_max_f32_e32 v18, v18, v18
	v_max_f32_e32 v17, v17, v18
	ds_bpermute_b32 v18, v29, v17
	s_waitcnt lgkmcnt(0)
	v_max_f32_e32 v18, v18, v18
	v_max_f32_e32 v17, v17, v18
	ds_bpermute_b32 v18, v30, v17
	s_and_b64 exec, exec, s[2:3]
	s_cbranch_execz .LBB0_1299
	s_addk_i32 s0, 0x8000
	s_waitcnt lgkmcnt(0)
	v_max_f32_e32 v18, v18, v18
	v_max_f32_e32 v17, v17, v17
	s_lshr_b32 s0, s0, 8
	v_max_f32_e32 v17, v17, v18
	s_ashr_i32 s1, s11, 5
	v_mov_b32_e32 v18, s0
	s_mov_b32 s0, 0x8000
	s_ashr_i32 s8, s4, 7
	v_mov_b32_e32 v19, s1
	v_cmp_gt_i32_e64 s[4:5], s0, v37
	s_ashr_i32 s9, s8, 31
	s_nop 0
	v_cndmask_b32_e64 v18, v18, v19, s[4:5]
	v_lshlrev_b32_e32 v18, 2, v18
	v_ashrrev_i32_e32 v19, 31, v18
	v_lshl_add_u64 v[18:19], v[18:19], 2, s[22:23]
	v_lshl_add_u64 v[18:19], s[8:9], 2, v[18:19]
	global_atomic_umax v[18:19], v17, off
	s_branch .LBB0_1299
